# EpiAct epilogues: SiLU section rewritten by hand, out = (g*u)*(s*s)/(1+exp2(g*s*-log2e)), 9 instead of 12 vector instructions per output pair, f32 throughout
# speedup vs baseline: 1.0118x; 1.0118x over previous
; #define PG8_GAS __attribute__((address_space(1)))
; __device__ __forceinline__ unsigned pk2_(float lo, float hi) { f32x2c_t v = {lo, hi}; bf16x2c_t b = __builtin_convertvector(v, bf16x2c_t); return __builtin_bit_cast(unsigned, b); }
; __device__ __forceinline__ float row_rstd(const float* parts, int r, int fq) {
;     const f32x4 p = *(const PG8_GAS f32x4*)(parts + (size_t)r * 16 + 4 * fq);
;     float s = (p[0] + p[1]) + (p[2] + p[3]);
;     s += __shfl_xor(s, 16); s += __shfl_xor(s, 32);
;     return rsqrtf(s * (1.0f / 1024.0f) + RMS_EPS);
; }
; __device__ __forceinline__ float silu_f(float x) { return x * __builtin_amdgcn_rcpf(1.0f + __builtin_amdgcn_exp2f(-1.4426950408889634f * x)); }
;     __device__ __forceinline__ void operator()(const f32x4 (&acc)[2][2][4][2], const Unit& u, int wr, int wc, int fr, int fq) const {
;         const int row0 = u.pm * BM + wr * 64 + fr, col0 = u.pn * 128 + wc * 32 + 8 * fq;
;         float rs8[2][4];
; #pragma unroll
;         for (int ai = 0; ai < 2; ++ai)
; #pragma unroll
;             for (int m = 0; m < 4; ++m) rs8[ai][m] = row_rstd(parts, row0 + ai * HALF + m * 16, fq);
; #pragma unroll
;         for (int ai = 0; ai < 2; ++ai)
; #pragma unroll
;             for (int m = 0; m < 4; ++m) {
;                 const int r = row0 + ai * HALF + m * 16; const float s = rs8[ai][m];
;                 float o[8];
; #pragma unroll
;                 for (int n = 0; n < 2; ++n)
; #pragma unroll
;                     for (int i = 0; i < 4; ++i) o[4 * n + i] = silu_f(acc[ai][0][m][n][i] * s) * (acc[ai][1][m][n][i] * s);
;                 u32x4 w; w.x = pk2_(o[0], o[1]); w.y = pk2_(o[2], o[3]); w.z = pk2_(o[4], o[5]); w.w = pk2_(o[6], o[7]);
;                 *(PG8_GAS u32x4*)(O + (size_t)r * 2816 + col0) = w;
.LBB0_697:
	s_lshl_b32 s6, s6, 8
	v_mov_b32_e32 v132, v252
	s_add_i32 s6, s6, s53
	s_sub_i32 s99, s6, s53
	s_mov_b32 s98, s53
	s_lshl_b32 s100, s99, 6
	s_add_u32 s100, s80, s100
	s_addc_u32 s101, s81, 0
	v_lshrrev_b32_e32 v143, 6, v252
	v_and_b32_e32 v141, 63, v252
	v_lshlrev_b32_e32 v141, 4, v141
	v_lshl_or_b32 v141, v143, 11, v141
	global_load_dwordx4 v[168:171], v141, s[100:101]
	global_load_dwordx4 v[176:179], v141, s[100:101] offset:1024
	v_bfe_u32 v200, v132, 4, 2
	v_and_or_b32 v160, v132, 15, s6
	v_lshlrev_b32_e32 v132, 4, v200
	v_ashrrev_i32_e32 v161, 31, v160
	v_or_b32_e32 v156, 16, v160
	v_lshl_add_u64 v[190:191], s[80:81], 0, v[132:133]
	v_ashrrev_i32_e32 v157, 31, v156
	v_or_b32_e32 v152, 32, v160
	v_ashrrev_i32_e32 v153, 31, v152
	v_or_b32_e32 v148, 48, v160
	v_ashrrev_i32_e32 v149, 31, v148
	v_add_u32_e32 v146, 0x80, v160
	v_ashrrev_i32_e32 v147, 31, v146
	v_add_u32_e32 v144, 0x90, v160
	v_ashrrev_i32_e32 v145, 31, v144
	v_and_b32_e32 v140, 64, v165
	v_add_u32_e32 v147, 64, v140
	v_add_u32_e32 v142, 0xa0, v160
	v_add_u32_e32 v140, 0xb0, v160
	v_xor_b32_e32 v132, 16, v165
	v_cmp_lt_i32_e32 vcc, v132, v147
	v_xor_b32_e32 v145, 32, v165
	s_nop 0
	v_cndmask_b32_e32 v132, v165, v132, vcc
	v_lshlrev_b32_e32 v132, 2, v132
	v_cmp_lt_i32_e32 vcc, v145, v147
	v_mov_b64_e32 v[174:175], s[28:29]
	s_waitcnt vmcnt(0)
	v_add_f32_e32 v168, v168, v169
	v_add_f32_e32 v170, v170, v171
	v_add_f32_e32 v176, v176, v177
	v_add_f32_e32 v178, v178, v179
	v_add_f32_e32 v168, v168, v170
	v_add_f32_e32 v176, v176, v178
	v_mov_b32_e32 v170, 0x358637bd
	s_nop 0
	v_add_f32_dpp v169, v168, v168 quad_perm:[1,0,3,2] row_mask:0xf bank_mask:0xf
	v_add_f32_dpp v177, v176, v176 quad_perm:[1,0,3,2] row_mask:0xf bank_mask:0xf
	v_and_b32_e32 v171, 60, v252
	v_lshl_add_u32 v171, v143, 7, v171
	v_add_f32_dpp v168, v169, v169 quad_perm:[2,3,0,1] row_mask:0xf bank_mask:0xf
	v_add_f32_dpp v176, v177, v177 quad_perm:[2,3,0,1] row_mask:0xf bank_mask:0xf
	v_add_u32_e32 v171, 0x21000, v171
	v_and_b32_e32 v178, 15, v252
	v_fmamk_f32 v168, v168, 0x3a800000, v170
	v_fmamk_f32 v176, v176, 0x3a800000, v170
	v_add_u32_e32 v178, s98, v178
	v_rsq_f32_e32 v168, v168
	v_rsq_f32_e32 v176, v176
	v_lshlrev_b32_e32 v178, 2, v178
	v_add_u32_e32 v178, 0x21000, v178
	ds_write_b32 v171, v168
	ds_write_b32 v171, v176 offset:64
	s_waitcnt lgkmcnt(0)
	s_barrier
	ds_read_b32 v166, v178
	ds_read_b32 v172, v178 offset:64
	ds_read_b32 v164, v178 offset:128
	ds_read_b32 v162, v178 offset:192
	ds_read_b32 v158, v178 offset:512
	ds_read_b32 v154, v178 offset:576
	ds_read_b32 v150, v178 offset:640
	ds_read_b32 v132, v178 offset:704
	s_waitcnt lgkmcnt(0)
	s_lshl_b32 s6, s60, 7
	v_lshl_or_b32 v141, v200, 3, s6
	v_or_b32_e32 v168, s54, v141
	v_ashrrev_i32_e32 v169, 31, v168
	v_lshlrev_b64 v[168:169], 1, v[168:169]
	v_mov_b64_e32 v[170:171], s[14:15]
	v_mul_f32_e32 v174, 0xbfb8aa3b, v166
	v_mul_f32_e32 v175, v166, v166
	v_pk_mul_f32 v[116:117], v[124:125], v[116:117]
	v_pk_mul_f32 v[118:119], v[126:127], v[118:119]
	v_pk_mul_f32 v[124:125], v[124:125], v[174:175] op_sel_hi:[1,0]
	v_pk_mul_f32 v[126:127], v[126:127], v[174:175] op_sel_hi:[1,0]
	v_exp_f32_e32 v124, v124
	v_exp_f32_e32 v125, v125
	v_exp_f32_e32 v126, v126
	v_exp_f32_e32 v127, v127
	v_pk_add_f32 v[124:125], v[124:125], 1.0 op_sel_hi:[1,0]
	v_pk_mul_f32 v[116:117], v[116:117], v[174:175] op_sel:[0,1] op_sel_hi:[1,1]
	v_pk_add_f32 v[126:127], v[126:127], 1.0 op_sel_hi:[1,0]
	v_rcp_f32_e32 v124, v124
	v_rcp_f32_e32 v125, v125
	v_pk_mul_f32 v[118:119], v[118:119], v[174:175] op_sel:[0,1] op_sel_hi:[1,1]
	v_rcp_f32_e32 v126, v126
	v_rcp_f32_e32 v127, v127
	v_pk_mul_f32 v[116:117], v[116:117], v[124:125]
	s_nop 0
	v_pk_mul_f32 v[118:119], v[118:119], v[126:127]
	v_pk_mul_f32 v[112:113], v[120:121], v[112:113]
	v_pk_mul_f32 v[114:115], v[122:123], v[114:115]
	v_pk_mul_f32 v[120:121], v[120:121], v[174:175] op_sel_hi:[1,0]
	v_pk_mul_f32 v[122:123], v[122:123], v[174:175] op_sel_hi:[1,0]
	v_exp_f32_e32 v120, v120
	v_exp_f32_e32 v121, v121
	v_exp_f32_e32 v122, v122
	v_exp_f32_e32 v123, v123
	v_pk_add_f32 v[120:121], v[120:121], 1.0 op_sel_hi:[1,0]
	v_pk_mul_f32 v[112:113], v[112:113], v[174:175] op_sel:[0,1] op_sel_hi:[1,1]
	v_pk_add_f32 v[122:123], v[122:123], 1.0 op_sel_hi:[1,0]
	v_rcp_f32_e32 v120, v120
	v_rcp_f32_e32 v121, v121
	v_pk_mul_f32 v[114:115], v[114:115], v[174:175] op_sel:[0,1] op_sel_hi:[1,1]
	v_rcp_f32_e32 v122, v122
	v_rcp_f32_e32 v123, v123
	v_pk_mul_f32 v[112:113], v[112:113], v[120:121]
	s_nop 0
	v_pk_mul_f32 v[114:115], v[114:115], v[122:123]
	v_cvt_pk_bf16_f32 v116, v116, v117
	v_cvt_pk_bf16_f32 v117, v118, v119
	v_cvt_pk_bf16_f32 v118, v112, v113
	v_cvt_pk_bf16_f32 v119, v114, v115
	v_mad_i64_i32 v[120:121], s[6:7], v160, s59, v[170:171]
	v_lshl_add_u64 v[120:121], v[120:121], 0, v[168:169]
	global_store_dwordx4 v[120:121], v[116:119], off
	v_mul_f32_e32 v174, 0xbfb8aa3b, v172
	v_mul_f32_e32 v175, v172, v172
	v_pk_mul_f32 v[100:101], v[108:109], v[100:101]
	v_pk_mul_f32 v[102:103], v[110:111], v[102:103]
	v_pk_mul_f32 v[108:109], v[108:109], v[174:175] op_sel_hi:[1,0]
	v_pk_mul_f32 v[110:111], v[110:111], v[174:175] op_sel_hi:[1,0]
	v_exp_f32_e32 v108, v108
	v_exp_f32_e32 v109, v109
	v_exp_f32_e32 v110, v110
	v_exp_f32_e32 v111, v111
	v_pk_add_f32 v[108:109], v[108:109], 1.0 op_sel_hi:[1,0]
	v_pk_mul_f32 v[100:101], v[100:101], v[174:175] op_sel:[0,1] op_sel_hi:[1,1]
	v_pk_add_f32 v[110:111], v[110:111], 1.0 op_sel_hi:[1,0]
	v_rcp_f32_e32 v108, v108
	v_rcp_f32_e32 v109, v109
	v_pk_mul_f32 v[102:103], v[102:103], v[174:175] op_sel:[0,1] op_sel_hi:[1,1]
	v_rcp_f32_e32 v110, v110
	v_rcp_f32_e32 v111, v111
; #define PG8_GAS __attribute__((address_space(1)))
; __device__ __forceinline__ unsigned pk2_(float lo, float hi) { f32x2c_t v = {lo, hi}; bf16x2c_t b = __builtin_convertvector(v, bf16x2c_t); return __builtin_bit_cast(unsigned, b); }
; __device__ __forceinline__ float silu_f(float x) { return x * __builtin_amdgcn_rcpf(1.0f + __builtin_amdgcn_exp2f(-1.4426950408889634f * x)); }
;     __device__ __forceinline__ void operator()(const f32x4 (&acc)[2][2][4][2], const Unit& u, int wr, int wc, int fr, int fq) const {
;     ...
;                 const int r = row0 + ai * HALF + m * 16; const float s = rs8[ai][m];
;                 float o[8];
; #pragma unroll
;                 for (int n = 0; n < 2; ++n)
; #pragma unroll
;                     for (int i = 0; i < 4; ++i) o[4 * n + i] = silu_f(acc[ai][0][m][n][i] * s) * (acc[ai][1][m][n][i] * s);
;                 u32x4 w; w.x = pk2_(o[0], o[1]); w.y = pk2_(o[2], o[3]); w.z = pk2_(o[4], o[5]); w.w = pk2_(o[6], o[7]);
;                 *(PG8_GAS u32x4*)(O + (size_t)r * 2816 + col0) = w;
	v_pk_mul_f32 v[100:101], v[100:101], v[108:109]
	s_nop 0
	v_pk_mul_f32 v[102:103], v[102:103], v[110:111]
	v_pk_mul_f32 v[96:97], v[104:105], v[96:97]
	v_pk_mul_f32 v[98:99], v[106:107], v[98:99]
	v_pk_mul_f32 v[104:105], v[104:105], v[174:175] op_sel_hi:[1,0]
	v_pk_mul_f32 v[106:107], v[106:107], v[174:175] op_sel_hi:[1,0]
	v_exp_f32_e32 v104, v104
	v_exp_f32_e32 v105, v105
	v_exp_f32_e32 v106, v106
	v_exp_f32_e32 v107, v107
	v_pk_add_f32 v[104:105], v[104:105], 1.0 op_sel_hi:[1,0]
	v_pk_mul_f32 v[96:97], v[96:97], v[174:175] op_sel:[0,1] op_sel_hi:[1,1]
	v_pk_add_f32 v[106:107], v[106:107], 1.0 op_sel_hi:[1,0]
	v_rcp_f32_e32 v104, v104
	v_rcp_f32_e32 v105, v105
	v_pk_mul_f32 v[98:99], v[98:99], v[174:175] op_sel:[0,1] op_sel_hi:[1,1]
	v_rcp_f32_e32 v106, v106
	v_rcp_f32_e32 v107, v107
	v_pk_mul_f32 v[96:97], v[96:97], v[104:105]
	s_nop 0
	v_pk_mul_f32 v[98:99], v[98:99], v[106:107]
	v_cvt_pk_bf16_f32 v100, v100, v101
	v_cvt_pk_bf16_f32 v101, v102, v103
	v_cvt_pk_bf16_f32 v102, v96, v97
	v_cvt_pk_bf16_f32 v103, v98, v99
	v_mad_i64_i32 v[104:105], s[6:7], v156, s59, v[170:171]
	v_lshl_add_u64 v[104:105], v[104:105], 0, v[168:169]
	global_store_dwordx4 v[104:105], v[100:103], off
	v_mul_f32_e32 v174, 0xbfb8aa3b, v164
	v_mul_f32_e32 v175, v164, v164
	v_pk_mul_f32 v[84:85], v[92:93], v[84:85]
	v_pk_mul_f32 v[86:87], v[94:95], v[86:87]
	v_pk_mul_f32 v[92:93], v[92:93], v[174:175] op_sel_hi:[1,0]
	v_pk_mul_f32 v[94:95], v[94:95], v[174:175] op_sel_hi:[1,0]
	v_exp_f32_e32 v92, v92
	v_exp_f32_e32 v93, v93
	v_exp_f32_e32 v94, v94
	v_exp_f32_e32 v95, v95
	v_pk_add_f32 v[92:93], v[92:93], 1.0 op_sel_hi:[1,0]
	v_pk_mul_f32 v[84:85], v[84:85], v[174:175] op_sel:[0,1] op_sel_hi:[1,1]
	v_pk_add_f32 v[94:95], v[94:95], 1.0 op_sel_hi:[1,0]
	v_rcp_f32_e32 v92, v92
	v_rcp_f32_e32 v93, v93
	v_pk_mul_f32 v[86:87], v[86:87], v[174:175] op_sel:[0,1] op_sel_hi:[1,1]
	v_rcp_f32_e32 v94, v94
	v_rcp_f32_e32 v95, v95
	v_pk_mul_f32 v[84:85], v[84:85], v[92:93]
	s_nop 0
	v_pk_mul_f32 v[86:87], v[86:87], v[94:95]
	v_pk_mul_f32 v[80:81], v[88:89], v[80:81]
	v_pk_mul_f32 v[82:83], v[90:91], v[82:83]
	v_pk_mul_f32 v[88:89], v[88:89], v[174:175] op_sel_hi:[1,0]
	v_pk_mul_f32 v[90:91], v[90:91], v[174:175] op_sel_hi:[1,0]
	v_exp_f32_e32 v88, v88
	v_exp_f32_e32 v89, v89
	v_exp_f32_e32 v90, v90
	v_exp_f32_e32 v91, v91
	v_pk_add_f32 v[88:89], v[88:89], 1.0 op_sel_hi:[1,0]
	v_pk_mul_f32 v[80:81], v[80:81], v[174:175] op_sel:[0,1] op_sel_hi:[1,1]
	v_pk_add_f32 v[90:91], v[90:91], 1.0 op_sel_hi:[1,0]
	v_rcp_f32_e32 v88, v88
	v_rcp_f32_e32 v89, v89
	v_pk_mul_f32 v[82:83], v[82:83], v[174:175] op_sel:[0,1] op_sel_hi:[1,1]
	v_rcp_f32_e32 v90, v90
	v_rcp_f32_e32 v91, v91
	v_pk_mul_f32 v[80:81], v[80:81], v[88:89]
	s_nop 0
	v_pk_mul_f32 v[82:83], v[82:83], v[90:91]
	v_cvt_pk_bf16_f32 v84, v84, v85
	v_cvt_pk_bf16_f32 v85, v86, v87
	v_cvt_pk_bf16_f32 v86, v80, v81
	v_cvt_pk_bf16_f32 v87, v82, v83
	v_mad_i64_i32 v[88:89], s[6:7], v152, s59, v[170:171]
	v_lshl_add_u64 v[88:89], v[88:89], 0, v[168:169]
	global_store_dwordx4 v[88:89], v[84:87], off
	v_mul_f32_e32 v174, 0xbfb8aa3b, v162
	v_mul_f32_e32 v175, v162, v162
	v_pk_mul_f32 v[68:69], v[76:77], v[68:69]
	v_pk_mul_f32 v[70:71], v[78:79], v[70:71]
	v_pk_mul_f32 v[76:77], v[76:77], v[174:175] op_sel_hi:[1,0]
	v_pk_mul_f32 v[78:79], v[78:79], v[174:175] op_sel_hi:[1,0]
	v_exp_f32_e32 v76, v76
	v_exp_f32_e32 v77, v77
	v_exp_f32_e32 v78, v78
	v_exp_f32_e32 v79, v79
	v_pk_add_f32 v[76:77], v[76:77], 1.0 op_sel_hi:[1,0]
	v_pk_mul_f32 v[68:69], v[68:69], v[174:175] op_sel:[0,1] op_sel_hi:[1,1]
	v_pk_add_f32 v[78:79], v[78:79], 1.0 op_sel_hi:[1,0]
	v_rcp_f32_e32 v76, v76
	v_rcp_f32_e32 v77, v77
	v_pk_mul_f32 v[70:71], v[70:71], v[174:175] op_sel:[0,1] op_sel_hi:[1,1]
	v_rcp_f32_e32 v78, v78
	v_rcp_f32_e32 v79, v79
	v_pk_mul_f32 v[68:69], v[68:69], v[76:77]
	s_nop 0
	v_pk_mul_f32 v[70:71], v[70:71], v[78:79]
	v_pk_mul_f32 v[64:65], v[72:73], v[64:65]
	v_pk_mul_f32 v[66:67], v[74:75], v[66:67]
	v_pk_mul_f32 v[72:73], v[72:73], v[174:175] op_sel_hi:[1,0]
	v_pk_mul_f32 v[74:75], v[74:75], v[174:175] op_sel_hi:[1,0]
	v_exp_f32_e32 v72, v72
	v_exp_f32_e32 v73, v73
	v_exp_f32_e32 v74, v74
	v_exp_f32_e32 v75, v75
	v_pk_add_f32 v[72:73], v[72:73], 1.0 op_sel_hi:[1,0]
	v_pk_mul_f32 v[64:65], v[64:65], v[174:175] op_sel:[0,1] op_sel_hi:[1,1]
	v_pk_add_f32 v[74:75], v[74:75], 1.0 op_sel_hi:[1,0]
	v_rcp_f32_e32 v72, v72
	v_rcp_f32_e32 v73, v73
	v_pk_mul_f32 v[66:67], v[66:67], v[174:175] op_sel:[0,1] op_sel_hi:[1,1]
	v_rcp_f32_e32 v74, v74
	v_rcp_f32_e32 v75, v75
	v_pk_mul_f32 v[64:65], v[64:65], v[72:73]
	s_nop 0
	v_pk_mul_f32 v[66:67], v[66:67], v[74:75]
	v_cvt_pk_bf16_f32 v68, v68, v69
	v_cvt_pk_bf16_f32 v69, v70, v71
	v_cvt_pk_bf16_f32 v70, v64, v65
	v_cvt_pk_bf16_f32 v71, v66, v67
	v_mad_i64_i32 v[72:73], s[6:7], v148, s59, v[170:171]
	v_lshl_add_u64 v[72:73], v[72:73], 0, v[168:169]
	global_store_dwordx4 v[72:73], v[68:71], off
	v_mul_f32_e32 v174, 0xbfb8aa3b, v158
	v_mul_f32_e32 v175, v158, v158
	v_pk_mul_f32 v[52:53], v[60:61], v[52:53]
	v_pk_mul_f32 v[54:55], v[62:63], v[54:55]
	v_pk_mul_f32 v[60:61], v[60:61], v[174:175] op_sel_hi:[1,0]
	v_pk_mul_f32 v[62:63], v[62:63], v[174:175] op_sel_hi:[1,0]
	v_exp_f32_e32 v60, v60
	v_exp_f32_e32 v61, v61
	v_exp_f32_e32 v62, v62
	v_exp_f32_e32 v63, v63
	v_pk_add_f32 v[60:61], v[60:61], 1.0 op_sel_hi:[1,0]
	v_pk_mul_f32 v[52:53], v[52:53], v[174:175] op_sel:[0,1] op_sel_hi:[1,1]
	v_pk_add_f32 v[62:63], v[62:63], 1.0 op_sel_hi:[1,0]
	v_rcp_f32_e32 v60, v60
	v_rcp_f32_e32 v61, v61
	v_pk_mul_f32 v[54:55], v[54:55], v[174:175] op_sel:[0,1] op_sel_hi:[1,1]
	v_rcp_f32_e32 v62, v62
	v_rcp_f32_e32 v63, v63
; #define PG8_GAS __attribute__((address_space(1)))
; __device__ __forceinline__ unsigned pk2_(float lo, float hi) { f32x2c_t v = {lo, hi}; bf16x2c_t b = __builtin_convertvector(v, bf16x2c_t); return __builtin_bit_cast(unsigned, b); }
; __device__ __forceinline__ float silu_f(float x) { return x * __builtin_amdgcn_rcpf(1.0f + __builtin_amdgcn_exp2f(-1.4426950408889634f * x)); }
; #define PG8_BAR __builtin_amdgcn_s_barrier()
;     __device__ __forceinline__ void operator()(const f32x4 (&acc)[2][2][4][2], const Unit& u, int wr, int wc, int fr, int fq) const {
;     ...
;                 const int r = row0 + ai * HALF + m * 16; const float s = rs8[ai][m];
;                 float o[8];
; #pragma unroll
;                 for (int n = 0; n < 2; ++n)
; #pragma unroll
;                     for (int i = 0; i < 4; ++i) o[4 * n + i] = silu_f(acc[ai][0][m][n][i] * s) * (acc[ai][1][m][n][i] * s);
;                 u32x4 w; w.x = pk2_(o[0], o[1]); w.y = pk2_(o[2], o[3]); w.z = pk2_(o[4], o[5]); w.w = pk2_(o[6], o[7]);
;                 *(PG8_GAS u32x4*)(O + (size_t)r * 2816 + col0) = w;
; template <class Epi, class Sched, bool ALIGN_EPI = false, bool SP2 = false>
; __device__ __forceinline__ void gemm_phase(PG8_LAS unsigned char* lds, const Gemm g, const Sched& S, const Epi& E) {
;     ...
;         if constexpr (!Epi::AFTER_DRAIN) { int t2 = threadIdx.x; asm volatile("" : "+v"(t2)); E(acc, cur, wr, wc, t2 & 15, (t2 >> 4) & 3); S.done(cur); }
;         if (!has_next) break;
; #pragma unroll
;         for (int a = 0; a < 2; ++a)
; #pragma unroll
;             for (int b = 0; b < 2; ++b)
; #pragma unroll
;                 for (int m = 0; m < 4; ++m)
; #pragma unroll
;                     for (int n = 0; n < 2; ++n) acc[a][b][m][n] = (f32x4){0.f, 0.f, 0.f, 0.f};
;         cur = nxt; cA = nA; cB = nB; ++ui;
;         if constexpr (ALIGN_EPI) { if (wr == 1) PG8_BAR; }
	v_pk_mul_f32 v[52:53], v[52:53], v[60:61]
	s_nop 0
	v_pk_mul_f32 v[54:55], v[54:55], v[62:63]
	v_pk_mul_f32 v[48:49], v[56:57], v[48:49]
	v_pk_mul_f32 v[50:51], v[58:59], v[50:51]
	v_pk_mul_f32 v[56:57], v[56:57], v[174:175] op_sel_hi:[1,0]
	v_pk_mul_f32 v[58:59], v[58:59], v[174:175] op_sel_hi:[1,0]
	v_exp_f32_e32 v56, v56
	v_exp_f32_e32 v57, v57
	v_exp_f32_e32 v58, v58
	v_exp_f32_e32 v59, v59
	v_pk_add_f32 v[56:57], v[56:57], 1.0 op_sel_hi:[1,0]
	v_pk_mul_f32 v[48:49], v[48:49], v[174:175] op_sel:[0,1] op_sel_hi:[1,1]
	v_pk_add_f32 v[58:59], v[58:59], 1.0 op_sel_hi:[1,0]
	v_rcp_f32_e32 v56, v56
	v_rcp_f32_e32 v57, v57
	v_pk_mul_f32 v[50:51], v[50:51], v[174:175] op_sel:[0,1] op_sel_hi:[1,1]
	v_rcp_f32_e32 v58, v58
	v_rcp_f32_e32 v59, v59
	v_pk_mul_f32 v[48:49], v[48:49], v[56:57]
	s_nop 0
	v_pk_mul_f32 v[50:51], v[50:51], v[58:59]
	v_cvt_pk_bf16_f32 v52, v52, v53
	v_cvt_pk_bf16_f32 v53, v54, v55
	v_cvt_pk_bf16_f32 v54, v48, v49
	v_cvt_pk_bf16_f32 v55, v50, v51
	v_mad_i64_i32 v[56:57], s[6:7], v146, s59, v[170:171]
	v_lshl_add_u64 v[56:57], v[56:57], 0, v[168:169]
	global_store_dwordx4 v[56:57], v[52:55], off
	v_mul_f32_e32 v174, 0xbfb8aa3b, v154
	v_mul_f32_e32 v175, v154, v154
	v_pk_mul_f32 v[36:37], v[44:45], v[36:37]
	v_pk_mul_f32 v[38:39], v[46:47], v[38:39]
	v_pk_mul_f32 v[44:45], v[44:45], v[174:175] op_sel_hi:[1,0]
	v_pk_mul_f32 v[46:47], v[46:47], v[174:175] op_sel_hi:[1,0]
	v_exp_f32_e32 v44, v44
	v_exp_f32_e32 v45, v45
	v_exp_f32_e32 v46, v46
	v_exp_f32_e32 v47, v47
	v_pk_add_f32 v[44:45], v[44:45], 1.0 op_sel_hi:[1,0]
	v_pk_mul_f32 v[36:37], v[36:37], v[174:175] op_sel:[0,1] op_sel_hi:[1,1]
	v_pk_add_f32 v[46:47], v[46:47], 1.0 op_sel_hi:[1,0]
	v_rcp_f32_e32 v44, v44
	v_rcp_f32_e32 v45, v45
	v_pk_mul_f32 v[38:39], v[38:39], v[174:175] op_sel:[0,1] op_sel_hi:[1,1]
	v_rcp_f32_e32 v46, v46
	v_rcp_f32_e32 v47, v47
	v_pk_mul_f32 v[36:37], v[36:37], v[44:45]
	s_nop 0
	v_pk_mul_f32 v[38:39], v[38:39], v[46:47]
	v_pk_mul_f32 v[32:33], v[40:41], v[32:33]
	v_pk_mul_f32 v[34:35], v[42:43], v[34:35]
	v_pk_mul_f32 v[40:41], v[40:41], v[174:175] op_sel_hi:[1,0]
	v_pk_mul_f32 v[42:43], v[42:43], v[174:175] op_sel_hi:[1,0]
	v_exp_f32_e32 v40, v40
	v_exp_f32_e32 v41, v41
	v_exp_f32_e32 v42, v42
	v_exp_f32_e32 v43, v43
	v_pk_add_f32 v[40:41], v[40:41], 1.0 op_sel_hi:[1,0]
	v_pk_mul_f32 v[32:33], v[32:33], v[174:175] op_sel:[0,1] op_sel_hi:[1,1]
	v_pk_add_f32 v[42:43], v[42:43], 1.0 op_sel_hi:[1,0]
	v_rcp_f32_e32 v40, v40
	v_rcp_f32_e32 v41, v41
	v_pk_mul_f32 v[34:35], v[34:35], v[174:175] op_sel:[0,1] op_sel_hi:[1,1]
	v_rcp_f32_e32 v42, v42
	v_rcp_f32_e32 v43, v43
	v_pk_mul_f32 v[32:33], v[32:33], v[40:41]
	s_nop 0
	v_pk_mul_f32 v[34:35], v[34:35], v[42:43]
	v_cvt_pk_bf16_f32 v36, v36, v37
	v_cvt_pk_bf16_f32 v37, v38, v39
	v_cvt_pk_bf16_f32 v38, v32, v33
	v_cvt_pk_bf16_f32 v39, v34, v35
	v_mad_i64_i32 v[40:41], s[6:7], v144, s59, v[170:171]
	v_lshl_add_u64 v[40:41], v[40:41], 0, v[168:169]
	global_store_dwordx4 v[40:41], v[36:39], off
	v_mul_f32_e32 v174, 0xbfb8aa3b, v150
	v_mul_f32_e32 v175, v150, v150
	v_pk_mul_f32 v[20:21], v[28:29], v[20:21]
	v_pk_mul_f32 v[22:23], v[30:31], v[22:23]
	v_pk_mul_f32 v[28:29], v[28:29], v[174:175] op_sel_hi:[1,0]
	v_pk_mul_f32 v[30:31], v[30:31], v[174:175] op_sel_hi:[1,0]
	v_exp_f32_e32 v28, v28
	v_exp_f32_e32 v29, v29
	v_exp_f32_e32 v30, v30
	v_exp_f32_e32 v31, v31
	v_pk_add_f32 v[28:29], v[28:29], 1.0 op_sel_hi:[1,0]
	v_pk_mul_f32 v[20:21], v[20:21], v[174:175] op_sel:[0,1] op_sel_hi:[1,1]
	v_pk_add_f32 v[30:31], v[30:31], 1.0 op_sel_hi:[1,0]
	v_rcp_f32_e32 v28, v28
	v_rcp_f32_e32 v29, v29
	v_pk_mul_f32 v[22:23], v[22:23], v[174:175] op_sel:[0,1] op_sel_hi:[1,1]
	v_rcp_f32_e32 v30, v30
	v_rcp_f32_e32 v31, v31
	v_pk_mul_f32 v[20:21], v[20:21], v[28:29]
	s_nop 0
	v_pk_mul_f32 v[22:23], v[22:23], v[30:31]
	v_pk_mul_f32 v[16:17], v[24:25], v[16:17]
	v_pk_mul_f32 v[18:19], v[26:27], v[18:19]
	v_pk_mul_f32 v[24:25], v[24:25], v[174:175] op_sel_hi:[1,0]
	v_pk_mul_f32 v[26:27], v[26:27], v[174:175] op_sel_hi:[1,0]
	v_exp_f32_e32 v24, v24
	v_exp_f32_e32 v25, v25
	v_exp_f32_e32 v26, v26
	v_exp_f32_e32 v27, v27
	v_pk_add_f32 v[24:25], v[24:25], 1.0 op_sel_hi:[1,0]
	v_pk_mul_f32 v[16:17], v[16:17], v[174:175] op_sel:[0,1] op_sel_hi:[1,1]
	v_pk_add_f32 v[26:27], v[26:27], 1.0 op_sel_hi:[1,0]
	v_rcp_f32_e32 v24, v24
	v_rcp_f32_e32 v25, v25
	v_pk_mul_f32 v[18:19], v[18:19], v[174:175] op_sel:[0,1] op_sel_hi:[1,1]
	v_rcp_f32_e32 v26, v26
	v_rcp_f32_e32 v27, v27
	v_pk_mul_f32 v[16:17], v[16:17], v[24:25]
	s_nop 0
	v_pk_mul_f32 v[18:19], v[18:19], v[26:27]
	v_cvt_pk_bf16_f32 v20, v20, v21
	v_cvt_pk_bf16_f32 v21, v22, v23
	v_cvt_pk_bf16_f32 v22, v16, v17
	v_cvt_pk_bf16_f32 v23, v18, v19
	v_mad_i64_i32 v[24:25], s[6:7], v142, s59, v[170:171]
	v_lshl_add_u64 v[24:25], v[24:25], 0, v[168:169]
	global_store_dwordx4 v[24:25], v[20:23], off
	v_mul_f32_e32 v174, 0xbfb8aa3b, v132
	v_mul_f32_e32 v175, v132, v132
	v_pk_mul_f32 v[4:5], v[12:13], v[4:5]
	v_pk_mul_f32 v[6:7], v[14:15], v[6:7]
	v_pk_mul_f32 v[12:13], v[12:13], v[174:175] op_sel_hi:[1,0]
	v_pk_mul_f32 v[14:15], v[14:15], v[174:175] op_sel_hi:[1,0]
	v_exp_f32_e32 v12, v12
	v_exp_f32_e32 v13, v13
	v_exp_f32_e32 v14, v14
	v_exp_f32_e32 v15, v15
	v_pk_add_f32 v[12:13], v[12:13], 1.0 op_sel_hi:[1,0]
	v_pk_mul_f32 v[4:5], v[4:5], v[174:175] op_sel:[0,1] op_sel_hi:[1,1]
	v_pk_add_f32 v[14:15], v[14:15], 1.0 op_sel_hi:[1,0]
	v_rcp_f32_e32 v12, v12
	v_rcp_f32_e32 v13, v13
	v_pk_mul_f32 v[6:7], v[6:7], v[174:175] op_sel:[0,1] op_sel_hi:[1,1]
	v_rcp_f32_e32 v14, v14
	v_rcp_f32_e32 v15, v15
	v_pk_mul_f32 v[4:5], v[4:5], v[12:13]
	s_nop 0
	v_pk_mul_f32 v[6:7], v[6:7], v[14:15]
	v_pk_mul_f32 v[0:1], v[8:9], v[0:1]
	v_pk_mul_f32 v[2:3], v[10:11], v[2:3]
	v_pk_mul_f32 v[8:9], v[8:9], v[174:175] op_sel_hi:[1,0]
	v_pk_mul_f32 v[10:11], v[10:11], v[174:175] op_sel_hi:[1,0]
	v_exp_f32_e32 v8, v8
	v_exp_f32_e32 v9, v9
	v_exp_f32_e32 v10, v10
	v_exp_f32_e32 v11, v11
	v_pk_add_f32 v[8:9], v[8:9], 1.0 op_sel_hi:[1,0]
	v_pk_mul_f32 v[0:1], v[0:1], v[174:175] op_sel:[0,1] op_sel_hi:[1,1]
	v_pk_add_f32 v[10:11], v[10:11], 1.0 op_sel_hi:[1,0]
	v_rcp_f32_e32 v8, v8
	v_rcp_f32_e32 v9, v9
	v_pk_mul_f32 v[2:3], v[2:3], v[174:175] op_sel:[0,1] op_sel_hi:[1,1]
	v_rcp_f32_e32 v10, v10
	v_rcp_f32_e32 v11, v11
	v_pk_mul_f32 v[0:1], v[0:1], v[8:9]
	s_nop 0
	v_pk_mul_f32 v[2:3], v[2:3], v[10:11]
	v_cvt_pk_bf16_f32 v4, v4, v5
	v_cvt_pk_bf16_f32 v5, v6, v7
	v_cvt_pk_bf16_f32 v6, v0, v1
	v_cvt_pk_bf16_f32 v7, v2, v3
	v_mad_i64_i32 v[8:9], s[6:7], v140, s59, v[170:171]
	v_lshl_add_u64 v[8:9], v[8:9], 0, v[168:169]
	s_andn2_b64 vcc, exec, s[4:5]
	s_mov_b64 s[4:5], -1
	global_store_dwordx4 v[8:9], v[4:7], off
	s_cbranch_vccnz .LBB0_690
	s_andn2_b64 vcc, exec, s[12:13]
	s_cbranch_vccnz .LBB0_689
	s_barrier
	s_branch .LBB0_689

; #define PG8_GAS __attribute__((address_space(1)))
; __device__ __forceinline__ unsigned pk2_(float lo, float hi) { f32x2c_t v = {lo, hi}; bf16x2c_t b = __builtin_convertvector(v, bf16x2c_t); return __builtin_bit_cast(unsigned, b); }
; __device__ __forceinline__ float row_rstd(const float* parts, int r, int fq) {
;     const f32x4 p = *(const PG8_GAS f32x4*)(parts + (size_t)r * 16 + 4 * fq);
;     float s = (p[0] + p[1]) + (p[2] + p[3]);
;     s += __shfl_xor(s, 16); s += __shfl_xor(s, 32);
;     return rsqrtf(s * (1.0f / 1024.0f) + RMS_EPS);
; }
; __device__ __forceinline__ float silu_f(float x) { return x * __builtin_amdgcn_rcpf(1.0f + __builtin_amdgcn_exp2f(-1.4426950408889634f * x)); }
;     __device__ __forceinline__ void operator()(const f32x4 (&acc)[2][2][4][2], const Unit& u, int wr, int wc, int fr, int fq) const {
;         const int row0 = u.pm * BM + wr * 64 + fr, col0 = u.pn * 128 + wc * 32 + 8 * fq;
;         float rs8[2][4];
; #pragma unroll
;         for (int ai = 0; ai < 2; ++ai)
; #pragma unroll
;             for (int m = 0; m < 4; ++m) rs8[ai][m] = row_rstd(parts, row0 + ai * HALF + m * 16, fq);
; #pragma unroll
;         for (int ai = 0; ai < 2; ++ai)
; #pragma unroll
;             for (int m = 0; m < 4; ++m) {
;                 const int r = row0 + ai * HALF + m * 16; const float s = rs8[ai][m];
;                 float o[8];
; #pragma unroll
;                 for (int n = 0; n < 2; ++n)
; #pragma unroll
;                     for (int i = 0; i < 4; ++i) o[4 * n + i] = silu_f(acc[ai][0][m][n][i] * s) * (acc[ai][1][m][n][i] * s);
;                 u32x4 w; w.x = pk2_(o[0], o[1]); w.y = pk2_(o[2], o[3]); w.z = pk2_(o[4], o[5]); w.w = pk2_(o[6], o[7]);
;                 *(PG8_GAS u32x4*)(O + (size_t)r * 2816 + col0) = w;
.LBB0_1661:
	s_lshl_b32 s8, s8, 8
	v_mov_b32_e32 v132, v252
	s_add_i32 s8, s8, s56
	s_sub_i32 s99, s8, s56
	s_mov_b32 s98, s56
	s_lshl_b32 s100, s99, 6
	s_add_u32 s100, s16, s100
	s_addc_u32 s101, s17, 0
	v_lshrrev_b32_e32 v143, 6, v252
	v_and_b32_e32 v141, 63, v252
	v_lshlrev_b32_e32 v141, 4, v141
	v_lshl_or_b32 v141, v143, 11, v141
	global_load_dwordx4 v[174:177], v141, s[100:101]
	global_load_dwordx4 v[178:181], v141, s[100:101] offset:1024
	v_cmp_lt_i32_e32 vcc, v227, v226
	v_bfe_u32 v200, v132, 4, 2
	v_and_or_b32 v160, v132, 15, s8
	v_lshlrev_b32_e32 v132, 4, v200
	v_ashrrev_i32_e32 v161, 31, v160
	v_or_b32_e32 v156, 16, v160
	v_lshl_add_u64 v[188:189], s[16:17], 0, v[132:133]
	v_ashrrev_i32_e32 v157, 31, v156
	v_or_b32_e32 v152, 32, v160
	v_ashrrev_i32_e32 v153, 31, v152
	v_or_b32_e32 v150, 48, v160
	v_ashrrev_i32_e32 v151, 31, v150
	v_add_u32_e32 v146, 0x80, v160
	v_ashrrev_i32_e32 v147, 31, v146
	v_add_u32_e32 v144, 0x90, v160
	v_ashrrev_i32_e32 v145, 31, v144
	v_add_u32_e32 v142, 0xa0, v160
	v_add_u32_e32 v140, 0xb0, v160
	v_cndmask_b32_e32 v132, v253, v227, vcc
	v_lshlrev_b32_e32 v132, 2, v132
	v_xor_b32_e32 v145, 32, v253
	v_cmp_lt_i32_e32 vcc, v145, v226
	v_mov_b64_e32 v[196:197], s[30:31]
	s_waitcnt vmcnt(0)
	v_add_f32_e32 v174, v174, v175
	v_add_f32_e32 v176, v176, v177
	v_add_f32_e32 v178, v178, v179
	v_add_f32_e32 v180, v180, v181
	v_add_f32_e32 v174, v174, v176
	v_add_f32_e32 v178, v178, v180
	v_mov_b32_e32 v176, 0x358637bd
	s_nop 0
	v_add_f32_dpp v175, v174, v174 quad_perm:[1,0,3,2] row_mask:0xf bank_mask:0xf
	v_add_f32_dpp v179, v178, v178 quad_perm:[1,0,3,2] row_mask:0xf bank_mask:0xf
	v_and_b32_e32 v177, 60, v252
	v_lshl_add_u32 v177, v143, 7, v177
	v_add_f32_dpp v174, v175, v175 quad_perm:[2,3,0,1] row_mask:0xf bank_mask:0xf
	v_add_f32_dpp v178, v179, v179 quad_perm:[2,3,0,1] row_mask:0xf bank_mask:0xf
	v_add_u32_e32 v177, 0x21000, v177
	v_and_b32_e32 v180, 15, v252
	v_fmamk_f32 v174, v174, 0x3a800000, v176
	v_fmamk_f32 v178, v178, 0x3a800000, v176
	v_add_u32_e32 v180, s98, v180
	v_rsq_f32_e32 v174, v174
	v_rsq_f32_e32 v178, v178
	v_lshlrev_b32_e32 v180, 2, v180
	v_add_u32_e32 v180, 0x21000, v180
	ds_write_b32 v177, v174
	ds_write_b32 v177, v178 offset:64
	s_waitcnt lgkmcnt(0)
	s_barrier
	ds_read_b32 v168, v180
	ds_read_b32 v172, v180 offset:64
	ds_read_b32 v164, v180 offset:128
	ds_read_b32 v162, v180 offset:192
	ds_read_b32 v158, v180 offset:512
	ds_read_b32 v154, v180 offset:576
	ds_read_b32 v148, v180 offset:640
	ds_read_b32 v132, v180 offset:704
	s_waitcnt lgkmcnt(0)
	s_lshl_b32 s8, s63, 7
	v_lshl_or_b32 v141, v200, 3, s8
	v_or_b32_e32 v166, s57, v141
	v_ashrrev_i32_e32 v167, 31, v166
	v_lshlrev_b64 v[166:167], 1, v[166:167]
	v_mov_b64_e32 v[170:171], s[14:15]
	v_mul_f32_e32 v174, 0xbfb8aa3b, v168
	v_mul_f32_e32 v175, v168, v168
	v_pk_mul_f32 v[116:117], v[124:125], v[116:117]
	v_pk_mul_f32 v[118:119], v[126:127], v[118:119]
	v_pk_mul_f32 v[124:125], v[124:125], v[174:175] op_sel_hi:[1,0]
	v_pk_mul_f32 v[126:127], v[126:127], v[174:175] op_sel_hi:[1,0]
	v_exp_f32_e32 v124, v124
	v_exp_f32_e32 v125, v125
	v_exp_f32_e32 v126, v126
	v_exp_f32_e32 v127, v127
	v_pk_add_f32 v[124:125], v[124:125], 1.0 op_sel_hi:[1,0]
	v_pk_mul_f32 v[116:117], v[116:117], v[174:175] op_sel:[0,1] op_sel_hi:[1,1]
	v_pk_add_f32 v[126:127], v[126:127], 1.0 op_sel_hi:[1,0]
	v_rcp_f32_e32 v124, v124
	v_rcp_f32_e32 v125, v125
	v_pk_mul_f32 v[118:119], v[118:119], v[174:175] op_sel:[0,1] op_sel_hi:[1,1]
	v_rcp_f32_e32 v126, v126
	v_rcp_f32_e32 v127, v127
	v_pk_mul_f32 v[116:117], v[116:117], v[124:125]
	s_nop 0
	v_pk_mul_f32 v[118:119], v[118:119], v[126:127]
	v_pk_mul_f32 v[112:113], v[120:121], v[112:113]
	v_pk_mul_f32 v[114:115], v[122:123], v[114:115]
	v_pk_mul_f32 v[120:121], v[120:121], v[174:175] op_sel_hi:[1,0]
	v_pk_mul_f32 v[122:123], v[122:123], v[174:175] op_sel_hi:[1,0]
	v_exp_f32_e32 v120, v120
	v_exp_f32_e32 v121, v121
	v_exp_f32_e32 v122, v122
	v_exp_f32_e32 v123, v123
	v_pk_add_f32 v[120:121], v[120:121], 1.0 op_sel_hi:[1,0]
	v_pk_mul_f32 v[112:113], v[112:113], v[174:175] op_sel:[0,1] op_sel_hi:[1,1]
	v_pk_add_f32 v[122:123], v[122:123], 1.0 op_sel_hi:[1,0]
	v_rcp_f32_e32 v120, v120
	v_rcp_f32_e32 v121, v121
	v_pk_mul_f32 v[114:115], v[114:115], v[174:175] op_sel:[0,1] op_sel_hi:[1,1]
	v_rcp_f32_e32 v122, v122
	v_rcp_f32_e32 v123, v123
	v_pk_mul_f32 v[112:113], v[112:113], v[120:121]
	s_nop 0
	v_pk_mul_f32 v[114:115], v[114:115], v[122:123]
	v_cvt_pk_bf16_f32 v116, v116, v117
	v_cvt_pk_bf16_f32 v117, v118, v119
	v_cvt_pk_bf16_f32 v118, v112, v113
	v_cvt_pk_bf16_f32 v119, v114, v115
	v_mad_i64_i32 v[120:121], s[8:9], v160, s62, v[170:171]
	v_lshl_add_u64 v[120:121], v[120:121], 0, v[166:167]
	global_store_dwordx4 v[120:121], v[116:119], off
	v_mul_f32_e32 v174, 0xbfb8aa3b, v172
	v_mul_f32_e32 v175, v172, v172
	v_pk_mul_f32 v[100:101], v[108:109], v[100:101]
	v_pk_mul_f32 v[102:103], v[110:111], v[102:103]
	v_pk_mul_f32 v[108:109], v[108:109], v[174:175] op_sel_hi:[1,0]
	v_pk_mul_f32 v[110:111], v[110:111], v[174:175] op_sel_hi:[1,0]
	v_exp_f32_e32 v108, v108
	v_exp_f32_e32 v109, v109
	v_exp_f32_e32 v110, v110
	v_exp_f32_e32 v111, v111
	v_pk_add_f32 v[108:109], v[108:109], 1.0 op_sel_hi:[1,0]
	v_pk_mul_f32 v[100:101], v[100:101], v[174:175] op_sel:[0,1] op_sel_hi:[1,1]
	v_pk_add_f32 v[110:111], v[110:111], 1.0 op_sel_hi:[1,0]
	v_rcp_f32_e32 v108, v108
	v_rcp_f32_e32 v109, v109
	v_pk_mul_f32 v[102:103], v[102:103], v[174:175] op_sel:[0,1] op_sel_hi:[1,1]
	v_rcp_f32_e32 v110, v110
	v_rcp_f32_e32 v111, v111
	v_pk_mul_f32 v[100:101], v[100:101], v[108:109]
	s_nop 0
	v_pk_mul_f32 v[102:103], v[102:103], v[110:111]
; #define PG8_GAS __attribute__((address_space(1)))
; __device__ __forceinline__ unsigned pk2_(float lo, float hi) { f32x2c_t v = {lo, hi}; bf16x2c_t b = __builtin_convertvector(v, bf16x2c_t); return __builtin_bit_cast(unsigned, b); }
; __device__ __forceinline__ float silu_f(float x) { return x * __builtin_amdgcn_rcpf(1.0f + __builtin_amdgcn_exp2f(-1.4426950408889634f * x)); }
;     __device__ __forceinline__ void operator()(const f32x4 (&acc)[2][2][4][2], const Unit& u, int wr, int wc, int fr, int fq) const {
;     ...
;             for (int m = 0; m < 4; ++m) {
;                 const int r = row0 + ai * HALF + m * 16; const float s = rs8[ai][m];
;                 float o[8];
; #pragma unroll
;                 for (int n = 0; n < 2; ++n)
; #pragma unroll
;                     for (int i = 0; i < 4; ++i) o[4 * n + i] = silu_f(acc[ai][0][m][n][i] * s) * (acc[ai][1][m][n][i] * s);
;                 u32x4 w; w.x = pk2_(o[0], o[1]); w.y = pk2_(o[2], o[3]); w.z = pk2_(o[4], o[5]); w.w = pk2_(o[6], o[7]);
;                 *(PG8_GAS u32x4*)(O + (size_t)r * 2816 + col0) = w;
	v_pk_mul_f32 v[96:97], v[104:105], v[96:97]
	v_pk_mul_f32 v[98:99], v[106:107], v[98:99]
	v_pk_mul_f32 v[104:105], v[104:105], v[174:175] op_sel_hi:[1,0]
	v_pk_mul_f32 v[106:107], v[106:107], v[174:175] op_sel_hi:[1,0]
	v_exp_f32_e32 v104, v104
	v_exp_f32_e32 v105, v105
	v_exp_f32_e32 v106, v106
	v_exp_f32_e32 v107, v107
	v_pk_add_f32 v[104:105], v[104:105], 1.0 op_sel_hi:[1,0]
	v_pk_mul_f32 v[96:97], v[96:97], v[174:175] op_sel:[0,1] op_sel_hi:[1,1]
	v_pk_add_f32 v[106:107], v[106:107], 1.0 op_sel_hi:[1,0]
	v_rcp_f32_e32 v104, v104
	v_rcp_f32_e32 v105, v105
	v_pk_mul_f32 v[98:99], v[98:99], v[174:175] op_sel:[0,1] op_sel_hi:[1,1]
	v_rcp_f32_e32 v106, v106
	v_rcp_f32_e32 v107, v107
	v_pk_mul_f32 v[96:97], v[96:97], v[104:105]
	s_nop 0
	v_pk_mul_f32 v[98:99], v[98:99], v[106:107]
	v_cvt_pk_bf16_f32 v100, v100, v101
	v_cvt_pk_bf16_f32 v101, v102, v103
	v_cvt_pk_bf16_f32 v102, v96, v97
	v_cvt_pk_bf16_f32 v103, v98, v99
	v_mad_i64_i32 v[104:105], s[8:9], v156, s62, v[170:171]
	v_lshl_add_u64 v[104:105], v[104:105], 0, v[166:167]
	global_store_dwordx4 v[104:105], v[100:103], off
	v_mul_f32_e32 v174, 0xbfb8aa3b, v164
	v_mul_f32_e32 v175, v164, v164
	v_pk_mul_f32 v[84:85], v[92:93], v[84:85]
	v_pk_mul_f32 v[86:87], v[94:95], v[86:87]
	v_pk_mul_f32 v[92:93], v[92:93], v[174:175] op_sel_hi:[1,0]
	v_pk_mul_f32 v[94:95], v[94:95], v[174:175] op_sel_hi:[1,0]
	v_exp_f32_e32 v92, v92
	v_exp_f32_e32 v93, v93
	v_exp_f32_e32 v94, v94
	v_exp_f32_e32 v95, v95
	v_pk_add_f32 v[92:93], v[92:93], 1.0 op_sel_hi:[1,0]
	v_pk_mul_f32 v[84:85], v[84:85], v[174:175] op_sel:[0,1] op_sel_hi:[1,1]
	v_pk_add_f32 v[94:95], v[94:95], 1.0 op_sel_hi:[1,0]
	v_rcp_f32_e32 v92, v92
	v_rcp_f32_e32 v93, v93
	v_pk_mul_f32 v[86:87], v[86:87], v[174:175] op_sel:[0,1] op_sel_hi:[1,1]
	v_rcp_f32_e32 v94, v94
	v_rcp_f32_e32 v95, v95
	v_pk_mul_f32 v[84:85], v[84:85], v[92:93]
	s_nop 0
	v_pk_mul_f32 v[86:87], v[86:87], v[94:95]
	v_pk_mul_f32 v[80:81], v[88:89], v[80:81]
	v_pk_mul_f32 v[82:83], v[90:91], v[82:83]
	v_pk_mul_f32 v[88:89], v[88:89], v[174:175] op_sel_hi:[1,0]
	v_pk_mul_f32 v[90:91], v[90:91], v[174:175] op_sel_hi:[1,0]
	v_exp_f32_e32 v88, v88
	v_exp_f32_e32 v89, v89
	v_exp_f32_e32 v90, v90
	v_exp_f32_e32 v91, v91
	v_pk_add_f32 v[88:89], v[88:89], 1.0 op_sel_hi:[1,0]
	v_pk_mul_f32 v[80:81], v[80:81], v[174:175] op_sel:[0,1] op_sel_hi:[1,1]
	v_pk_add_f32 v[90:91], v[90:91], 1.0 op_sel_hi:[1,0]
	v_rcp_f32_e32 v88, v88
	v_rcp_f32_e32 v89, v89
	v_pk_mul_f32 v[82:83], v[82:83], v[174:175] op_sel:[0,1] op_sel_hi:[1,1]
	v_rcp_f32_e32 v90, v90
	v_rcp_f32_e32 v91, v91
	v_pk_mul_f32 v[80:81], v[80:81], v[88:89]
	s_nop 0
	v_pk_mul_f32 v[82:83], v[82:83], v[90:91]
	v_cvt_pk_bf16_f32 v84, v84, v85
	v_cvt_pk_bf16_f32 v85, v86, v87
	v_cvt_pk_bf16_f32 v86, v80, v81
	v_cvt_pk_bf16_f32 v87, v82, v83
	v_mad_i64_i32 v[88:89], s[8:9], v152, s62, v[170:171]
	v_lshl_add_u64 v[88:89], v[88:89], 0, v[166:167]
	global_store_dwordx4 v[88:89], v[84:87], off
	v_mul_f32_e32 v174, 0xbfb8aa3b, v162
	v_mul_f32_e32 v175, v162, v162
	v_pk_mul_f32 v[68:69], v[76:77], v[68:69]
	v_pk_mul_f32 v[70:71], v[78:79], v[70:71]
	v_pk_mul_f32 v[76:77], v[76:77], v[174:175] op_sel_hi:[1,0]
	v_pk_mul_f32 v[78:79], v[78:79], v[174:175] op_sel_hi:[1,0]
	v_exp_f32_e32 v76, v76
	v_exp_f32_e32 v77, v77
	v_exp_f32_e32 v78, v78
	v_exp_f32_e32 v79, v79
	v_pk_add_f32 v[76:77], v[76:77], 1.0 op_sel_hi:[1,0]
	v_pk_mul_f32 v[68:69], v[68:69], v[174:175] op_sel:[0,1] op_sel_hi:[1,1]
	v_pk_add_f32 v[78:79], v[78:79], 1.0 op_sel_hi:[1,0]
	v_rcp_f32_e32 v76, v76
	v_rcp_f32_e32 v77, v77
	v_pk_mul_f32 v[70:71], v[70:71], v[174:175] op_sel:[0,1] op_sel_hi:[1,1]
	v_rcp_f32_e32 v78, v78
	v_rcp_f32_e32 v79, v79
	v_pk_mul_f32 v[68:69], v[68:69], v[76:77]
	s_nop 0
	v_pk_mul_f32 v[70:71], v[70:71], v[78:79]
	v_pk_mul_f32 v[64:65], v[72:73], v[64:65]
	v_pk_mul_f32 v[66:67], v[74:75], v[66:67]
	v_pk_mul_f32 v[72:73], v[72:73], v[174:175] op_sel_hi:[1,0]
	v_pk_mul_f32 v[74:75], v[74:75], v[174:175] op_sel_hi:[1,0]
	v_exp_f32_e32 v72, v72
	v_exp_f32_e32 v73, v73
	v_exp_f32_e32 v74, v74
	v_exp_f32_e32 v75, v75
	v_pk_add_f32 v[72:73], v[72:73], 1.0 op_sel_hi:[1,0]
	v_pk_mul_f32 v[64:65], v[64:65], v[174:175] op_sel:[0,1] op_sel_hi:[1,1]
	v_pk_add_f32 v[74:75], v[74:75], 1.0 op_sel_hi:[1,0]
	v_rcp_f32_e32 v72, v72
	v_rcp_f32_e32 v73, v73
	v_pk_mul_f32 v[66:67], v[66:67], v[174:175] op_sel:[0,1] op_sel_hi:[1,1]
	v_rcp_f32_e32 v74, v74
	v_rcp_f32_e32 v75, v75
	v_pk_mul_f32 v[64:65], v[64:65], v[72:73]
	s_nop 0
	v_pk_mul_f32 v[66:67], v[66:67], v[74:75]
	v_cvt_pk_bf16_f32 v68, v68, v69
	v_cvt_pk_bf16_f32 v69, v70, v71
	v_cvt_pk_bf16_f32 v70, v64, v65
	v_cvt_pk_bf16_f32 v71, v66, v67
	v_mad_i64_i32 v[72:73], s[8:9], v150, s62, v[170:171]
	v_lshl_add_u64 v[72:73], v[72:73], 0, v[166:167]
	global_store_dwordx4 v[72:73], v[68:71], off
	v_mul_f32_e32 v174, 0xbfb8aa3b, v158
	v_mul_f32_e32 v175, v158, v158
	v_pk_mul_f32 v[52:53], v[60:61], v[52:53]
	v_pk_mul_f32 v[54:55], v[62:63], v[54:55]
	v_pk_mul_f32 v[60:61], v[60:61], v[174:175] op_sel_hi:[1,0]
	v_pk_mul_f32 v[62:63], v[62:63], v[174:175] op_sel_hi:[1,0]
	v_exp_f32_e32 v60, v60
	v_exp_f32_e32 v61, v61
	v_exp_f32_e32 v62, v62
	v_exp_f32_e32 v63, v63
	v_pk_add_f32 v[60:61], v[60:61], 1.0 op_sel_hi:[1,0]
	v_pk_mul_f32 v[52:53], v[52:53], v[174:175] op_sel:[0,1] op_sel_hi:[1,1]
	v_pk_add_f32 v[62:63], v[62:63], 1.0 op_sel_hi:[1,0]
	v_rcp_f32_e32 v60, v60
	v_rcp_f32_e32 v61, v61
	v_pk_mul_f32 v[54:55], v[54:55], v[174:175] op_sel:[0,1] op_sel_hi:[1,1]
	v_rcp_f32_e32 v62, v62
	v_rcp_f32_e32 v63, v63
	v_pk_mul_f32 v[52:53], v[52:53], v[60:61]
	s_nop 0
	v_pk_mul_f32 v[54:55], v[54:55], v[62:63]
; #define PG8_GAS __attribute__((address_space(1)))
; __device__ __forceinline__ unsigned pk2_(float lo, float hi) { f32x2c_t v = {lo, hi}; bf16x2c_t b = __builtin_convertvector(v, bf16x2c_t); return __builtin_bit_cast(unsigned, b); }
; __device__ __forceinline__ float silu_f(float x) { return x * __builtin_amdgcn_rcpf(1.0f + __builtin_amdgcn_exp2f(-1.4426950408889634f * x)); }
;     __device__ __forceinline__ void operator()(const f32x4 (&acc)[2][2][4][2], const Unit& u, int wr, int wc, int fr, int fq) const {
;     ...
;             for (int m = 0; m < 4; ++m) {
;                 const int r = row0 + ai * HALF + m * 16; const float s = rs8[ai][m];
;                 float o[8];
; #pragma unroll
;                 for (int n = 0; n < 2; ++n)
; #pragma unroll
;                     for (int i = 0; i < 4; ++i) o[4 * n + i] = silu_f(acc[ai][0][m][n][i] * s) * (acc[ai][1][m][n][i] * s);
;                 u32x4 w; w.x = pk2_(o[0], o[1]); w.y = pk2_(o[2], o[3]); w.z = pk2_(o[4], o[5]); w.w = pk2_(o[6], o[7]);
;                 *(PG8_GAS u32x4*)(O + (size_t)r * 2816 + col0) = w;
	v_pk_mul_f32 v[48:49], v[56:57], v[48:49]
	v_pk_mul_f32 v[50:51], v[58:59], v[50:51]
	v_pk_mul_f32 v[56:57], v[56:57], v[174:175] op_sel_hi:[1,0]
	v_pk_mul_f32 v[58:59], v[58:59], v[174:175] op_sel_hi:[1,0]
	v_exp_f32_e32 v56, v56
	v_exp_f32_e32 v57, v57
	v_exp_f32_e32 v58, v58
	v_exp_f32_e32 v59, v59
	v_pk_add_f32 v[56:57], v[56:57], 1.0 op_sel_hi:[1,0]
	v_pk_mul_f32 v[48:49], v[48:49], v[174:175] op_sel:[0,1] op_sel_hi:[1,1]
	v_pk_add_f32 v[58:59], v[58:59], 1.0 op_sel_hi:[1,0]
	v_rcp_f32_e32 v56, v56
	v_rcp_f32_e32 v57, v57
	v_pk_mul_f32 v[50:51], v[50:51], v[174:175] op_sel:[0,1] op_sel_hi:[1,1]
	v_rcp_f32_e32 v58, v58
	v_rcp_f32_e32 v59, v59
	v_pk_mul_f32 v[48:49], v[48:49], v[56:57]
	s_nop 0
	v_pk_mul_f32 v[50:51], v[50:51], v[58:59]
	v_cvt_pk_bf16_f32 v52, v52, v53
	v_cvt_pk_bf16_f32 v53, v54, v55
	v_cvt_pk_bf16_f32 v54, v48, v49
	v_cvt_pk_bf16_f32 v55, v50, v51
	v_mad_i64_i32 v[56:57], s[8:9], v146, s62, v[170:171]
	v_lshl_add_u64 v[56:57], v[56:57], 0, v[166:167]
	global_store_dwordx4 v[56:57], v[52:55], off
	v_mul_f32_e32 v174, 0xbfb8aa3b, v154
	v_mul_f32_e32 v175, v154, v154
	v_pk_mul_f32 v[36:37], v[44:45], v[36:37]
	v_pk_mul_f32 v[38:39], v[46:47], v[38:39]
	v_pk_mul_f32 v[44:45], v[44:45], v[174:175] op_sel_hi:[1,0]
	v_pk_mul_f32 v[46:47], v[46:47], v[174:175] op_sel_hi:[1,0]
	v_exp_f32_e32 v44, v44
	v_exp_f32_e32 v45, v45
	v_exp_f32_e32 v46, v46
	v_exp_f32_e32 v47, v47
	v_pk_add_f32 v[44:45], v[44:45], 1.0 op_sel_hi:[1,0]
	v_pk_mul_f32 v[36:37], v[36:37], v[174:175] op_sel:[0,1] op_sel_hi:[1,1]
	v_pk_add_f32 v[46:47], v[46:47], 1.0 op_sel_hi:[1,0]
	v_rcp_f32_e32 v44, v44
	v_rcp_f32_e32 v45, v45
	v_pk_mul_f32 v[38:39], v[38:39], v[174:175] op_sel:[0,1] op_sel_hi:[1,1]
	v_rcp_f32_e32 v46, v46
	v_rcp_f32_e32 v47, v47
	v_pk_mul_f32 v[36:37], v[36:37], v[44:45]
	s_nop 0
	v_pk_mul_f32 v[38:39], v[38:39], v[46:47]
	v_pk_mul_f32 v[32:33], v[40:41], v[32:33]
	v_pk_mul_f32 v[34:35], v[42:43], v[34:35]
	v_pk_mul_f32 v[40:41], v[40:41], v[174:175] op_sel_hi:[1,0]
	v_pk_mul_f32 v[42:43], v[42:43], v[174:175] op_sel_hi:[1,0]
	v_exp_f32_e32 v40, v40
	v_exp_f32_e32 v41, v41
	v_exp_f32_e32 v42, v42
	v_exp_f32_e32 v43, v43
	v_pk_add_f32 v[40:41], v[40:41], 1.0 op_sel_hi:[1,0]
	v_pk_mul_f32 v[32:33], v[32:33], v[174:175] op_sel:[0,1] op_sel_hi:[1,1]
	v_pk_add_f32 v[42:43], v[42:43], 1.0 op_sel_hi:[1,0]
	v_rcp_f32_e32 v40, v40
	v_rcp_f32_e32 v41, v41
	v_pk_mul_f32 v[34:35], v[34:35], v[174:175] op_sel:[0,1] op_sel_hi:[1,1]
	v_rcp_f32_e32 v42, v42
	v_rcp_f32_e32 v43, v43
	v_pk_mul_f32 v[32:33], v[32:33], v[40:41]
	s_nop 0
	v_pk_mul_f32 v[34:35], v[34:35], v[42:43]
	v_cvt_pk_bf16_f32 v36, v36, v37
	v_cvt_pk_bf16_f32 v37, v38, v39
	v_cvt_pk_bf16_f32 v38, v32, v33
	v_cvt_pk_bf16_f32 v39, v34, v35
	v_mad_i64_i32 v[40:41], s[8:9], v144, s62, v[170:171]
	v_lshl_add_u64 v[40:41], v[40:41], 0, v[166:167]
	global_store_dwordx4 v[40:41], v[36:39], off
	v_mul_f32_e32 v174, 0xbfb8aa3b, v148
	v_mul_f32_e32 v175, v148, v148
	v_pk_mul_f32 v[20:21], v[28:29], v[20:21]
	v_pk_mul_f32 v[22:23], v[30:31], v[22:23]
	v_pk_mul_f32 v[28:29], v[28:29], v[174:175] op_sel_hi:[1,0]
	v_pk_mul_f32 v[30:31], v[30:31], v[174:175] op_sel_hi:[1,0]
	v_exp_f32_e32 v28, v28
	v_exp_f32_e32 v29, v29
	v_exp_f32_e32 v30, v30
	v_exp_f32_e32 v31, v31
	v_pk_add_f32 v[28:29], v[28:29], 1.0 op_sel_hi:[1,0]
	v_pk_mul_f32 v[20:21], v[20:21], v[174:175] op_sel:[0,1] op_sel_hi:[1,1]
	v_pk_add_f32 v[30:31], v[30:31], 1.0 op_sel_hi:[1,0]
	v_rcp_f32_e32 v28, v28
	v_rcp_f32_e32 v29, v29
	v_pk_mul_f32 v[22:23], v[22:23], v[174:175] op_sel:[0,1] op_sel_hi:[1,1]
	v_rcp_f32_e32 v30, v30
	v_rcp_f32_e32 v31, v31
	v_pk_mul_f32 v[20:21], v[20:21], v[28:29]
	s_nop 0
	v_pk_mul_f32 v[22:23], v[22:23], v[30:31]
	v_pk_mul_f32 v[16:17], v[24:25], v[16:17]
	v_pk_mul_f32 v[18:19], v[26:27], v[18:19]
	v_pk_mul_f32 v[24:25], v[24:25], v[174:175] op_sel_hi:[1,0]
	v_pk_mul_f32 v[26:27], v[26:27], v[174:175] op_sel_hi:[1,0]
	v_exp_f32_e32 v24, v24
	v_exp_f32_e32 v25, v25
	v_exp_f32_e32 v26, v26
	v_exp_f32_e32 v27, v27
	v_pk_add_f32 v[24:25], v[24:25], 1.0 op_sel_hi:[1,0]
	v_pk_mul_f32 v[16:17], v[16:17], v[174:175] op_sel:[0,1] op_sel_hi:[1,1]
	v_pk_add_f32 v[26:27], v[26:27], 1.0 op_sel_hi:[1,0]
	v_rcp_f32_e32 v24, v24
	v_rcp_f32_e32 v25, v25
	v_pk_mul_f32 v[18:19], v[18:19], v[174:175] op_sel:[0,1] op_sel_hi:[1,1]
	v_rcp_f32_e32 v26, v26
	v_rcp_f32_e32 v27, v27
	v_pk_mul_f32 v[16:17], v[16:17], v[24:25]
	s_nop 0
	v_pk_mul_f32 v[18:19], v[18:19], v[26:27]
	v_cvt_pk_bf16_f32 v20, v20, v21
	v_cvt_pk_bf16_f32 v21, v22, v23
	v_cvt_pk_bf16_f32 v22, v16, v17
	v_cvt_pk_bf16_f32 v23, v18, v19
	v_mad_i64_i32 v[24:25], s[8:9], v142, s62, v[170:171]
	v_lshl_add_u64 v[24:25], v[24:25], 0, v[166:167]
	global_store_dwordx4 v[24:25], v[20:23], off
	v_mul_f32_e32 v174, 0xbfb8aa3b, v132
	v_mul_f32_e32 v175, v132, v132
	v_pk_mul_f32 v[4:5], v[12:13], v[4:5]
	v_pk_mul_f32 v[6:7], v[14:15], v[6:7]
	v_pk_mul_f32 v[12:13], v[12:13], v[174:175] op_sel_hi:[1,0]
	v_pk_mul_f32 v[14:15], v[14:15], v[174:175] op_sel_hi:[1,0]
	v_exp_f32_e32 v12, v12
	v_exp_f32_e32 v13, v13
	v_exp_f32_e32 v14, v14
	v_exp_f32_e32 v15, v15
	v_pk_add_f32 v[12:13], v[12:13], 1.0 op_sel_hi:[1,0]
	v_pk_mul_f32 v[4:5], v[4:5], v[174:175] op_sel:[0,1] op_sel_hi:[1,1]
	v_pk_add_f32 v[14:15], v[14:15], 1.0 op_sel_hi:[1,0]
	v_rcp_f32_e32 v12, v12
	v_rcp_f32_e32 v13, v13
	v_pk_mul_f32 v[6:7], v[6:7], v[174:175] op_sel:[0,1] op_sel_hi:[1,1]
	v_rcp_f32_e32 v14, v14
	v_rcp_f32_e32 v15, v15
	v_pk_mul_f32 v[4:5], v[4:5], v[12:13]
	s_nop 0
	v_pk_mul_f32 v[6:7], v[6:7], v[14:15]
	v_pk_mul_f32 v[0:1], v[8:9], v[0:1]
	v_pk_mul_f32 v[2:3], v[10:11], v[2:3]
	v_pk_mul_f32 v[8:9], v[8:9], v[174:175] op_sel_hi:[1,0]
	v_pk_mul_f32 v[10:11], v[10:11], v[174:175] op_sel_hi:[1,0]
	v_exp_f32_e32 v8, v8
	v_exp_f32_e32 v9, v9
	v_exp_f32_e32 v10, v10
	v_exp_f32_e32 v11, v11
	v_pk_add_f32 v[8:9], v[8:9], 1.0 op_sel_hi:[1,0]
	v_pk_mul_f32 v[0:1], v[0:1], v[174:175] op_sel:[0,1] op_sel_hi:[1,1]
	v_pk_add_f32 v[10:11], v[10:11], 1.0 op_sel_hi:[1,0]
	v_rcp_f32_e32 v8, v8
	v_rcp_f32_e32 v9, v9
	v_pk_mul_f32 v[2:3], v[2:3], v[174:175] op_sel:[0,1] op_sel_hi:[1,1]
	v_rcp_f32_e32 v10, v10
	v_rcp_f32_e32 v11, v11
	v_pk_mul_f32 v[0:1], v[0:1], v[8:9]
	s_nop 0
	v_pk_mul_f32 v[2:3], v[2:3], v[10:11]
	v_cvt_pk_bf16_f32 v4, v4, v5
	v_cvt_pk_bf16_f32 v5, v6, v7
	v_cvt_pk_bf16_f32 v6, v0, v1
	v_cvt_pk_bf16_f32 v7, v2, v3
	v_mad_i64_i32 v[8:9], s[8:9], v140, s62, v[170:171]
	v_lshl_add_u64 v[8:9], v[8:9], 0, v[166:167]
	s_andn2_b64 vcc, exec, s[6:7]
	s_mov_b64 s[6:7], -1
	global_store_dwordx4 v[8:9], v[4:7], off
	s_cbranch_vccnz .LBB0_1654
	s_andn2_b64 vcc, exec, s[12:13]
	s_cbranch_vccnz .LBB0_1653
	s_barrier
	s_branch .LBB0_1653
